# GEMM prologues: second batch of LDS-DMA stage loads issued before the first batch's wait+barrier (vmcnt 4 -> 10 moved down), both batches in flight together
# speedup vs baseline: 1.0031x; 1.0031x over previous
; #define PG8_STAGE(bufoff, gbase, voff) do { _Pragma("unroll") for (int _i = 0; _i < 2; ++_i) \
;         __builtin_amdgcn_global_load_lds((const unsigned*)((const char*)(gbase) + (voff)[_i]), (LAS unsigned*)(lds + (bufoff) + ldsw + _i * 8192), 16, 0, 0); } while (0)
; #define PG8_WAIT_V(n) asm volatile("s_waitcnt vmcnt(" #n ")" ::: "memory")
; #define PG8_BAR __builtin_amdgcn_s_barrier()
; template <class Epi>
; __device__ __forceinline__ void gemm_phase(LAS unsigned char* lds, const Gemm g, const StaticOrder& S, const Epi& E) {
;     ...
;     for (int i = 0; i < 2; ++i) { int R, C; stage_rc(tid * 16 + i * 8192, R, C); const int Rb = Epi::PERM ? ((R & ~31) + perm32(R & 31)) : R;
;         voffA[i] = (unsigned)(R * K + C) * 2u; voffB[i] = (unsigned)(Rb * K + C) * 2u; }
;     const size_t kstep = (size_t)(BK * 2);
;     const size_t hstep = (size_t)HALF * K * 2;
;     const size_t tstep = 2 * hstep;
;     const unsigned ldsw = (unsigned)wid * 1024u;
;     const int aoff = lds_byte(wr * 64 + fr, fq * 8), boff = lds_byte(wc * 32 + fr, fq * 8);
;     ...
;     const char* cA = (const char*)g.A + (size_t)cur.pm * tstep; const char* cB = (const char*)g.Bt + (size_t)cur.pn * tstep;
;     PG8_STAGE(PG8_SB(0, 0), cB, voffB); PG8_STAGE(PG8_SA(0, 0), cA, voffA); PG8_STAGE(PG8_SB(0, 1), cB + hstep, voffB); PG8_STAGE(PG8_SA(0, 1), cA + hstep, voffA);
;     if (wr == 1) PG8_BAR;
;     PG8_WAIT_V(4); PG8_BAR;
;     PG8_STAGE(PG8_SB(1, 0), cB + kstep, voffB); PG8_STAGE(PG8_SA(1, 0), cA + kstep, voffA); PG8_STAGE(PG8_SB(1, 1), cB + hstep + kstep, voffB);
;     PG8_WAIT_V(6); PG8_BAR;
.LBB0_128:
	s_add_u32 s0, s12, 0x4542000
	s_addc_u32 s1, s13, 0
	s_lshl_b32 s4, s4, 5
	s_and_b32 s11, s4, 0x60
	s_mov_b64 s[4:5], 0x80
	s_add_i32 m0, s17, 0x18000
	v_lshl_add_u64 v[6:7], v[6:7], 0, s[4:5]
	s_ashr_i32 s35, s94, 31
	s_ashr_i32 s50, s96, 31
	s_lshl_b32 s10, s3, 13
	s_lshl_b32 s18, s11, 7
	s_nop 0
	s_nop 0
	global_load_lds_dwordx4 v[6:7], off
	v_lshl_add_u64 v[4:5], v[4:5], 0, s[4:5]
	s_add_i32 m0, s17, 0x1a000
	s_add_i32 s51, s17, 0x8000
	s_add_i32 s54, s17, 0xa000
	global_load_lds_dwordx4 v[4:5], off
	v_lshl_add_u64 v[2:3], v[2:3], 0, s[4:5]
	s_mov_b32 m0, s51
	s_add_u32 s8, s24, 0x80080
	global_load_lds_dwordx4 v[2:3], off
	v_lshl_add_u64 v[0:1], v[0:1], 0, s[4:5]
	s_mov_b32 m0, s54
	s_addc_u32 s9, s25, 0
	global_load_lds_dwordx4 v[0:1], off
	s_add_i32 m0, s17, 0x1c000
	s_nop 0
	global_load_lds_dwordx4 v130, s[8:9]
	v_lshl_add_u64 v[0:1], s[8:9], 0, v[134:135]
	s_add_i32 m0, s17, 0x1e000
	s_sext_i32_i16 s72, s2
	global_load_lds_dwordx4 v[0:1], off
	v_lshlrev_b32_e32 v0, 1, v11
	v_lshlrev_b32_e32 v1, 6, v214
	s_movk_i32 s2, 0x3c0
	v_lshlrev_b32_e32 v2, 2, v214
	v_and_or_b32 v1, v1, s2, v0
	v_and_b32_e32 v2, 32, v2
	v_bitop3_b32 v152, s18, v1, v2 bitop3:0xf6
	v_lshlrev_b32_e32 v1, 9, v214
	v_and_b32_e32 v1, 0x70000, v1
	v_lshlrev_b32_e32 v2, 12, v10
	v_or3_b32 v1, v8, v1, v2
	v_lshlrev_b32_e32 v3, 2, v150
	v_add_u32_e32 v136, v1, v9
	v_lshlrev_b32_e32 v1, 5, v12
	v_lshl_or_b32 v0, v150, 6, v0
	v_and_b32_e32 v3, 32, v3
	s_waitcnt vmcnt(10)
	s_barrier
	s_waitcnt vmcnt(6)
	v_and_b32_e32 v1, 0xf0000, v1
	v_bitop3_b32 v0, v0, s10, v3 bitop3:0xde
	v_or3_b32 v1, v8, v1, v2
	s_add_i32 s69, 0, 0x10000
	s_add_i32 s70, 0, 0x14000
	s_mov_b32 s55, s96
	v_lshl_or_b32 v151, s3, 6, v150
	v_or_b32_e32 v153, s11, v11
	v_mov_b32_e32 v137, v131
	v_add_u32_e32 v138, v1, v9
	v_mov_b32_e32 v139, v131
	v_mov_b64_e32 v[140:141], 0x4a4
	v_mov_b64_e32 v[142:143], 0x4a3
	v_add_u32_e32 v154, s69, v152
	v_add_u32_e32 v155, 0, v0
	v_add_u32_e32 v156, s70, v152
	s_movk_i32 s71, 0x4800
	s_barrier

; #define PG8_STAGE(bufoff, gbase, voff) do { _Pragma("unroll") for (int _i = 0; _i < 2; ++_i) \
;         __builtin_amdgcn_global_load_lds((const unsigned*)((const char*)(gbase) + (voff)[_i]), (LAS unsigned*)(lds + (bufoff) + ldsw + _i * 8192), 16, 0, 0); } while (0)
; #define PG8_WAIT_V(n) asm volatile("s_waitcnt vmcnt(" #n ")" ::: "memory")
; #define PG8_BAR __builtin_amdgcn_s_barrier()
; template <class Epi>
; __device__ __forceinline__ void gemm_phase(LAS unsigned char* lds, const Gemm g, const StaticOrder& S, const Epi& E) {
;     ...
;     for (int i = 0; i < 2; ++i) { int R, C; stage_rc(tid * 16 + i * 8192, R, C); const int Rb = Epi::PERM ? ((R & ~31) + perm32(R & 31)) : R;
;         voffA[i] = (unsigned)(R * K + C) * 2u; voffB[i] = (unsigned)(Rb * K + C) * 2u; }
;     const size_t kstep = (size_t)(BK * 2);
;     const size_t hstep = (size_t)HALF * K * 2;
;     const size_t tstep = 2 * hstep;
;     const unsigned ldsw = (unsigned)wid * 1024u;
;     const int aoff = lds_byte(wr * 64 + fr, fq * 8), boff = lds_byte(wc * 32 + fr, fq * 8);
;     ...
;     const char* cA = (const char*)g.A + (size_t)cur.pm * tstep; const char* cB = (const char*)g.Bt + (size_t)cur.pn * tstep;
;     PG8_STAGE(PG8_SB(0, 0), cB, voffB); PG8_STAGE(PG8_SA(0, 0), cA, voffA); PG8_STAGE(PG8_SB(0, 1), cB + hstep, voffB); PG8_STAGE(PG8_SA(0, 1), cA + hstep, voffA);
;     if (wr == 1) PG8_BAR;
;     PG8_WAIT_V(4); PG8_BAR;
;     PG8_STAGE(PG8_SB(1, 0), cB + kstep, voffB); PG8_STAGE(PG8_SA(1, 0), cA + kstep, voffA); PG8_STAGE(PG8_SB(1, 1), cB + hstep + kstep, voffB);
;     PG8_WAIT_V(6); PG8_BAR;
.LBB0_731:
	s_add_u32 s4, s12, 0x3180000
	s_addc_u32 s5, s13, 0
	s_lshl_b32 s10, s10, 5
	s_and_b32 s19, s10, 0x60
	s_mov_b64 s[10:11], 0x80
	s_add_i32 m0, s31, 0x18000
	v_lshl_add_u64 v[6:7], v[6:7], 0, s[10:11]
	s_ashr_i32 s49, s94, 31
	s_ashr_i32 s50, s96, 31
	s_lshl_b32 s18, s3, 13
	s_lshl_b32 s20, s19, 7
	s_nop 0
	s_nop 0
	global_load_lds_dwordx4 v[6:7], off
	v_lshl_add_u64 v[4:5], v[4:5], 0, s[10:11]
	s_add_i32 m0, s31, 0x1a000
	s_add_i32 s51, s31, 0x8000
	s_add_i32 s54, s31, 0xa000
	global_load_lds_dwordx4 v[4:5], off
	v_lshl_add_u64 v[2:3], v[2:3], 0, s[10:11]
	s_mov_b32 m0, s51
	s_add_u32 s16, s40, 0x40080
	global_load_lds_dwordx4 v[2:3], off
	v_lshl_add_u64 v[0:1], v[0:1], 0, s[10:11]
	s_mov_b32 m0, s54
	s_addc_u32 s17, s41, 0
	global_load_lds_dwordx4 v[0:1], off
	s_add_i32 m0, s31, 0x1c000
	s_nop 0
	global_load_lds_dwordx4 v166, s[16:17]
	v_lshl_add_u64 v[0:1], s[16:17], 0, v[170:171]
	s_add_i32 m0, s31, 0x1e000
	s_sext_i32_i8 s58, s2
	global_load_lds_dwordx4 v[0:1], off
	v_lshlrev_b32_e32 v0, 1, v11
	v_lshlrev_b32_e32 v1, 6, v214
	s_movk_i32 s2, 0x3c0
	v_lshlrev_b32_e32 v2, 2, v214
	v_and_or_b32 v1, v1, s2, v0
	v_and_b32_e32 v2, 32, v2
	v_bitop3_b32 v196, s20, v1, v2 bitop3:0xf6
	v_lshlrev_b32_e32 v1, 8, v214
	v_and_b32_e32 v1, 0x38000, v1
	v_lshlrev_b32_e32 v2, 11, v10
	v_or3_b32 v1, v8, v1, v2
	v_lshlrev_b32_e32 v3, 2, v194
	v_add_u32_e32 v172, v1, v9
	v_lshlrev_b32_e32 v1, 4, v12
	v_lshl_or_b32 v0, v194, 6, v0
	v_and_b32_e32 v3, 32, v3
	s_waitcnt vmcnt(10)
	s_barrier
	s_waitcnt vmcnt(6)
	v_and_b32_e32 v1, 0x78000, v1
	v_bitop3_b32 v0, v0, s18, v3 bitop3:0xde
	v_or3_b32 v1, v8, v1, v2
	s_add_i32 s56, 0, 0x10000
	s_add_i32 s57, 0, 0x14000
	s_mov_b32 s55, s96
	v_lshl_or_b32 v195, s3, 6, v194
	v_or_b32_e32 v197, s19, v11
	v_mov_b32_e32 v173, v167
	v_add_u32_e32 v174, v1, v9
	v_mov_b32_e32 v175, v167
	v_mov_b64_e32 v[176:177], 0x84
	v_mov_b64_e32 v[178:179], 0x83
	v_add_u32_e32 v198, s56, v196
	v_add_u32_e32 v199, 0, v0
	v_add_u32_e32 v200, s57, v196
	s_mov_b64 s[16:17], 0x48000
	s_mov_b64 s[18:19], 0x50000
	s_mov_b64 s[20:21], 0x58000
	s_barrier

; #define PG8_STAGE(bufoff, gbase, voff) do { _Pragma("unroll") for (int _i = 0; _i < 2; ++_i) \
;         __builtin_amdgcn_global_load_lds((const unsigned*)((const char*)(gbase) + (voff)[_i]), (LAS unsigned*)(lds + (bufoff) + ldsw + _i * 8192), 16, 0, 0); } while (0)
; #define PG8_WAIT_V(n) asm volatile("s_waitcnt vmcnt(" #n ")" ::: "memory")
; #define PG8_BAR __builtin_amdgcn_s_barrier()
; template <class Epi>
; __device__ __forceinline__ void gemm_phase(LAS unsigned char* lds, const Gemm g, const StaticOrder& S, const Epi& E) {
;     ...
;     for (int i = 0; i < 2; ++i) { int R, C; stage_rc(tid * 16 + i * 8192, R, C); const int Rb = Epi::PERM ? ((R & ~31) + perm32(R & 31)) : R;
;         voffA[i] = (unsigned)(R * K + C) * 2u; voffB[i] = (unsigned)(Rb * K + C) * 2u; }
;     const size_t kstep = (size_t)(BK * 2);
;     const size_t hstep = (size_t)HALF * K * 2;
;     const size_t tstep = 2 * hstep;
;     const unsigned ldsw = (unsigned)wid * 1024u;
;     const int aoff = lds_byte(wr * 64 + fr, fq * 8), boff = lds_byte(wc * 32 + fr, fq * 8);
;     ...
;     const char* cA = (const char*)g.A + (size_t)cur.pm * tstep; const char* cB = (const char*)g.Bt + (size_t)cur.pn * tstep;
;     PG8_STAGE(PG8_SB(0, 0), cB, voffB); PG8_STAGE(PG8_SA(0, 0), cA, voffA); PG8_STAGE(PG8_SB(0, 1), cB + hstep, voffB); PG8_STAGE(PG8_SA(0, 1), cA + hstep, voffA);
;     if (wr == 1) PG8_BAR;
;     PG8_WAIT_V(4); PG8_BAR;
;     PG8_STAGE(PG8_SB(1, 0), cB + kstep, voffB); PG8_STAGE(PG8_SA(1, 0), cA + kstep, voffA); PG8_STAGE(PG8_SB(1, 1), cB + hstep + kstep, voffB);
;     PG8_WAIT_V(6); PG8_BAR;
.LBB0_906:
	s_lshl_b32 s10, s10, 5
	s_and_b32 s19, s10, 0x60
	s_mov_b64 s[10:11], 0x80
	s_add_i32 m0, s27, 0x18000
	v_lshl_add_u64 v[0:1], v[0:1], 0, s[10:11]
	s_lshl_b32 s18, s3, 13
	s_nop 0
	s_nop 0
	global_load_lds_dwordx4 v[0:1], off
	v_lshl_add_u64 v[0:1], v[2:3], 0, s[10:11]
	s_add_i32 m0, s27, 0x1a000
	s_add_i32 s55, s27, 0x8000
	s_add_i32 s56, s27, 0xa000
	global_load_lds_dwordx4 v[0:1], off
	v_lshl_add_u64 v[0:1], v[6:7], 0, s[10:11]
	s_mov_b32 m0, s55
	s_add_u32 s16, s30, 0x40080
	global_load_lds_dwordx4 v[0:1], off
	v_lshl_add_u64 v[0:1], v[4:5], 0, s[10:11]
	s_mov_b32 m0, s56
	s_addc_u32 s17, s31, 0
	global_load_lds_dwordx4 v[0:1], off
	s_add_i32 m0, s27, 0x1c000
	s_nop 0
	global_load_lds_dwordx4 v174, s[16:17]
	v_lshl_add_u64 v[0:1], s[16:17], 0, v[178:179]
	s_add_i32 m0, s27, 0x1e000
	v_lshlrev_b32_e32 v2, 11, v170
	global_load_lds_dwordx4 v[0:1], off
	v_lshlrev_b32_e32 v1, 2, v202
	v_lshl_or_b32 v0, v202, 6, v181
	v_and_b32_e32 v1, 32, v1
	v_bitop3_b32 v0, v0, s18, v1 bitop3:0xde
	v_lshlrev_b32_e32 v1, 8, v214
	v_and_b32_e32 v1, 0x38000, v1
	v_or3_b32 v1, v168, v1, v2
	v_add_u32_e32 v148, v1, v169
	v_lshlrev_b32_e32 v1, 4, v171
	s_waitcnt vmcnt(10)
	s_barrier
	s_waitcnt vmcnt(6)
	v_and_b32_e32 v1, 0x78000, v1
	v_lshl_or_b32 v184, s19, 7, v182
	v_mov_b32_e32 v149, 0
	v_or3_b32 v1, v168, v1, v2
	s_add_i32 s58, 0, 0x10000
	s_add_i32 s59, 0, 0x14000
	s_sext_i32_i8 s62, s2
	v_lshl_or_b32 v183, s3, 6, v202
	s_mov_b32 s57, 0
	v_or_b32_e32 v185, s19, v180
	v_add_u32_e32 v150, v1, v169
	v_mov_b32_e32 v151, v149
	v_mov_b64_e32 v[152:153], 0x100
	v_mov_b64_e32 v[154:155], 0xff
	v_add_u32_e32 v186, s58, v184
	v_add_u32_e32 v187, 0, v0
	v_add_u32_e32 v188, s59, v184
	s_movk_i32 s60, 0x2000
	s_movk_i32 s61, 0x4800
	s_mov_b64 s[16:17], 0x2800
	s_barrier

; #define PG8_STAGE(bufoff, gbase, voff) do { _Pragma("unroll") for (int _i = 0; _i < 2; ++_i) \
;         __builtin_amdgcn_global_load_lds((const unsigned*)((const char*)(gbase) + (voff)[_i]), (LAS unsigned*)(lds + (bufoff) + ldsw + _i * 8192), 16, 0, 0); } while (0)
; #define PG8_WAIT_V(n) asm volatile("s_waitcnt vmcnt(" #n ")" ::: "memory")
; #define PG8_BAR __builtin_amdgcn_s_barrier()
; template <class Epi>
; __device__ __forceinline__ void gemm_phase(LAS unsigned char* lds, const Gemm g, const StaticOrder& S, const Epi& E) {
;     ...
;     for (int i = 0; i < 2; ++i) { int R, C; stage_rc(tid * 16 + i * 8192, R, C); const int Rb = Epi::PERM ? ((R & ~31) + perm32(R & 31)) : R;
;         voffA[i] = (unsigned)(R * K + C) * 2u; voffB[i] = (unsigned)(Rb * K + C) * 2u; }
;     const size_t kstep = (size_t)(BK * 2);
;     const size_t hstep = (size_t)HALF * K * 2;
;     const size_t tstep = 2 * hstep;
;     const unsigned ldsw = (unsigned)wid * 1024u;
;     const int aoff = lds_byte(wr * 64 + fr, fq * 8), boff = lds_byte(wc * 32 + fr, fq * 8);
;     ...
;     const char* cA = (const char*)g.A + (size_t)cur.pm * tstep; const char* cB = (const char*)g.Bt + (size_t)cur.pn * tstep;
;     PG8_STAGE(PG8_SB(0, 0), cB, voffB); PG8_STAGE(PG8_SA(0, 0), cA, voffA); PG8_STAGE(PG8_SB(0, 1), cB + hstep, voffB); PG8_STAGE(PG8_SA(0, 1), cA + hstep, voffA);
;     if (wr == 1) PG8_BAR;
;     PG8_WAIT_V(4); PG8_BAR;
;     PG8_STAGE(PG8_SB(1, 0), cB + kstep, voffB); PG8_STAGE(PG8_SA(1, 0), cA + kstep, voffA); PG8_STAGE(PG8_SB(1, 1), cB + hstep + kstep, voffB);
;     PG8_WAIT_V(6); PG8_BAR;
.LBB0_922:
	s_lshl_b32 s6, s6, 5
	s_lshl_b32 s16, s3, 13
	s_and_b32 s17, s6, 0x60
	s_add_u32 s6, s12, 0x18042000
	s_mov_b64 s[8:9], 0x80
	s_addc_u32 s7, s13, 0
	s_add_i32 m0, s25, 0x18000
	v_lshl_add_u64 v[0:1], v[0:1], 0, s[8:9]
	s_nop 0
	s_nop 0
	global_load_lds_dwordx4 v[0:1], off
	v_lshl_add_u64 v[0:1], v[2:3], 0, s[8:9]
	s_add_i32 m0, s25, 0x1a000
	s_add_i32 s49, s25, 0x8000
	s_add_i32 s50, s25, 0xa000
	global_load_lds_dwordx4 v[0:1], off
	v_lshl_add_u64 v[0:1], v[6:7], 0, s[8:9]
	s_mov_b32 m0, s49
	s_add_u32 s10, s28, 0x40080
	global_load_lds_dwordx4 v[0:1], off
	v_lshl_add_u64 v[0:1], v[4:5], 0, s[8:9]
	s_mov_b32 m0, s50
	s_addc_u32 s11, s29, 0
	global_load_lds_dwordx4 v[0:1], off
	s_add_i32 m0, s25, 0x1c000
	v_lshl_add_u64 v[0:1], s[10:11], 0, v[174:175]
	global_load_lds_dwordx4 v[0:1], off
	v_lshl_add_u64 v[0:1], s[10:11], 0, v[178:179]
	s_add_i32 m0, s25, 0x1e000
	v_lshlrev_b32_e32 v203, 2, v202
	global_load_lds_dwordx4 v[0:1], off
	v_lshl_or_b32 v0, v202, 6, v181
	v_and_b32_e32 v1, 32, v203
	v_bitop3_b32 v0, v0, s16, v1 bitop3:0xde
	v_lshlrev_b32_e32 v1, 8, v214
	v_and_b32_e32 v1, 0x38000, v1
	v_lshlrev_b32_e32 v2, 11, v170
	v_or3_b32 v1, v168, v1, v2
	v_or_b32_e32 v206, s17, v180
	v_add_u32_e32 v180, v1, v169
	v_lshlrev_b32_e32 v1, 4, v171
	s_waitcnt vmcnt(10)
	s_barrier
	s_waitcnt vmcnt(6)
	v_and_b32_e32 v1, 0x78000, v1
	v_lshl_or_b32 v205, s17, 7, v182
	v_mov_b32_e32 v181, 0
	v_or3_b32 v1, v168, v1, v2
	s_add_i32 s51, 0, 0x10000
	s_add_i32 s54, 0, 0x14000
	s_sext_i32_i8 s57, s2
	v_lshl_or_b32 v204, s3, 6, v202
	v_add_u32_e32 v182, v1, v169
	v_mov_b32_e32 v183, v181
	v_mov_b64_e32 v[184:185], 0x100
	v_mov_b64_e32 v[186:187], 0xff
	v_add_u32_e32 v207, s51, v205
	v_add_u32_e32 v208, 0, v0
	v_add_u32_e32 v209, s54, v205
	s_movk_i32 s55, 0x4800
	s_mov_b64 s[10:11], 0x3800
	s_movk_i32 s56, 0x3000
	s_barrier

; #define PG8_STAGE(bufoff, gbase, voff) do { _Pragma("unroll") for (int _i = 0; _i < 2; ++_i) \
;         __builtin_amdgcn_global_load_lds((const unsigned*)((const char*)(gbase) + (voff)[_i]), (LAS unsigned*)(lds + (bufoff) + ldsw + _i * 8192), 16, 0, 0); } while (0)
; #define PG8_WAIT_V(n) asm volatile("s_waitcnt vmcnt(" #n ")" ::: "memory")
; #define PG8_BAR __builtin_amdgcn_s_barrier()
; template <class Epi>
; __device__ __forceinline__ void gemm_phase(LAS unsigned char* lds, const Gemm g, const StaticOrder& S, const Epi& E) {
;     ...
;     for (int i = 0; i < 2; ++i) { int R, C; stage_rc(tid * 16 + i * 8192, R, C); const int Rb = Epi::PERM ? ((R & ~31) + perm32(R & 31)) : R;
;         voffA[i] = (unsigned)(R * K + C) * 2u; voffB[i] = (unsigned)(Rb * K + C) * 2u; }
;     const size_t kstep = (size_t)(BK * 2);
;     const size_t hstep = (size_t)HALF * K * 2;
;     const size_t tstep = 2 * hstep;
;     const unsigned ldsw = (unsigned)wid * 1024u;
;     const int aoff = lds_byte(wr * 64 + fr, fq * 8), boff = lds_byte(wc * 32 + fr, fq * 8);
;     ...
;     const char* cA = (const char*)g.A + (size_t)cur.pm * tstep; const char* cB = (const char*)g.Bt + (size_t)cur.pn * tstep;
;     PG8_STAGE(PG8_SB(0, 0), cB, voffB); PG8_STAGE(PG8_SA(0, 0), cA, voffA); PG8_STAGE(PG8_SB(0, 1), cB + hstep, voffB); PG8_STAGE(PG8_SA(0, 1), cA + hstep, voffA);
;     if (wr == 1) PG8_BAR;
;     PG8_WAIT_V(4); PG8_BAR;
;     PG8_STAGE(PG8_SB(1, 0), cB + kstep, voffB); PG8_STAGE(PG8_SA(1, 0), cA + kstep, voffA); PG8_STAGE(PG8_SB(1, 1), cB + hstep + kstep, voffB);
;     PG8_WAIT_V(6); PG8_BAR;
.LBB0_996:
	s_add_u32 s4, s12, 0x1a142000
	s_addc_u32 s5, s13, 0
	s_lshl_b32 s3, s3, 5
	s_mov_b64 s[10:11], 0x80
	s_and_b32 s3, s3, 0x60
	s_add_i32 m0, s40, 0x18000
	v_lshl_add_u64 v[6:7], v[6:7], 0, s[10:11]
	s_ashr_i32 s46, s94, 31
	s_ashr_i32 s47, s96, 31
	s_lshl_b32 s1, s2, 13
	s_lshl_b32 s16, s3, 7
	s_nop 0
	s_nop 0
	global_load_lds_dwordx4 v[6:7], off
	v_lshl_add_u64 v[4:5], v[4:5], 0, s[10:11]
	s_add_i32 m0, s40, 0x1a000
	s_add_i32 s48, s40, 0x8000
	s_add_i32 s49, s40, 0xa000
	global_load_lds_dwordx4 v[4:5], off
	v_lshl_add_u64 v[2:3], v[2:3], 0, s[10:11]
	s_mov_b32 m0, s48
	s_add_u32 s18, s30, 0x80080
	global_load_lds_dwordx4 v[2:3], off
	v_lshl_add_u64 v[0:1], v[0:1], 0, s[10:11]
	s_mov_b32 m0, s49
	s_addc_u32 s19, s31, 0
	global_load_lds_dwordx4 v[0:1], off
	s_add_i32 m0, s40, 0x1c000
	s_nop 0
	global_load_lds_dwordx4 v178, s[18:19]
	v_lshl_add_u64 v[0:1], s[18:19], 0, v[182:183]
	s_add_i32 m0, s40, 0x1e000
	s_movk_i32 s18, 0x3c0
	global_load_lds_dwordx4 v[0:1], off
	v_lshlrev_b32_e32 v0, 1, v11
	v_lshlrev_b32_e32 v1, 6, v214
	v_lshlrev_b32_e32 v2, 2, v214
	v_and_b32_e32 v206, 15, v214
	v_and_or_b32 v1, v1, s18, v0
	v_and_b32_e32 v2, 32, v2
	v_lshl_or_b32 v0, v206, 6, v0
	v_bitop3_b32 v208, s16, v1, v2 bitop3:0xf6
	v_lshlrev_b32_e32 v1, 9, v214
	v_bitop3_b32 v0, v0, s1, v2 bitop3:0xde
	v_and_b32_e32 v1, 0x70000, v1
	v_lshlrev_b32_e32 v2, 12, v10
	v_or3_b32 v1, v8, v1, v2
	v_add_u32_e32 v186, v1, v9
	v_lshlrev_b32_e32 v1, 5, v12
	s_waitcnt vmcnt(10)
	s_barrier
	s_waitcnt vmcnt(6)
	v_and_b32_e32 v1, 0xf0000, v1
	v_or3_b32 v1, v8, v1, v2
	s_add_i32 s51, 0, 0x10000
	s_add_i32 s54, 0, 0x14000
	s_mov_b32 s50, s96
	v_lshl_or_b32 v207, s2, 6, v206
	v_or_b32_e32 v209, s3, v11
	v_mov_b32_e32 v187, v185
	v_add_u32_e32 v188, v1, v9
	v_mov_b32_e32 v189, v185
	v_mov_b64_e32 v[190:191], 0x100
	v_mov_b64_e32 v[192:193], 0xff
	v_add_u32_e32 v210, s51, v208
	v_add_u32_e32 v211, 0, v0
	v_add_u32_e32 v212, s54, v208
	s_movk_i32 s55, 0x2080
	s_mov_b32 s16, 0x3f9837f0
	s_movk_i32 s56, 0x1f70
	s_movk_i32 s57, 0x1f60
	s_movk_i32 s58, 0x1f50
	s_movk_i32 s59, 0x1f80
	s_movk_i32 s60, 0x1ff0
	s_movk_i32 s61, 0x1fe0
	s_movk_i32 s62, 0x1fd0
	s_barrier
	s_branch .LBB0_998

; #define PG8_STAGE(bufoff, gbase, voff) do { _Pragma("unroll") for (int _i = 0; _i < 2; ++_i) \
;         __builtin_amdgcn_global_load_lds((const unsigned*)((const char*)(gbase) + (voff)[_i]), (LAS unsigned*)(lds + (bufoff) + ldsw + _i * 8192), 16, 0, 0); } while (0)
; #define PG8_WAIT_V(n) asm volatile("s_waitcnt vmcnt(" #n ")" ::: "memory")
; #define PG8_BAR __builtin_amdgcn_s_barrier()
; template <class Epi>
; __device__ __forceinline__ void gemm_phase(LAS unsigned char* lds, const Gemm g, const StaticOrder& S, const Epi& E) {
;     ...
;     for (int i = 0; i < 2; ++i) { int R, C; stage_rc(tid * 16 + i * 8192, R, C); const int Rb = Epi::PERM ? ((R & ~31) + perm32(R & 31)) : R;
;         voffA[i] = (unsigned)(R * K + C) * 2u; voffB[i] = (unsigned)(Rb * K + C) * 2u; }
;     const size_t kstep = (size_t)(BK * 2);
;     const size_t hstep = (size_t)HALF * K * 2;
;     const size_t tstep = 2 * hstep;
;     const unsigned ldsw = (unsigned)wid * 1024u;
;     const int aoff = lds_byte(wr * 64 + fr, fq * 8), boff = lds_byte(wc * 32 + fr, fq * 8);
;     ...
;     const char* cA = (const char*)g.A + (size_t)cur.pm * tstep; const char* cB = (const char*)g.Bt + (size_t)cur.pn * tstep;
;     PG8_STAGE(PG8_SB(0, 0), cB, voffB); PG8_STAGE(PG8_SA(0, 0), cA, voffA); PG8_STAGE(PG8_SB(0, 1), cB + hstep, voffB); PG8_STAGE(PG8_SA(0, 1), cA + hstep, voffA);
;     if (wr == 1) PG8_BAR;
;     PG8_WAIT_V(4); PG8_BAR;
;     PG8_STAGE(PG8_SB(1, 0), cB + kstep, voffB); PG8_STAGE(PG8_SA(1, 0), cA + kstep, voffA); PG8_STAGE(PG8_SB(1, 1), cB + hstep + kstep, voffB);
;     PG8_WAIT_V(6); PG8_BAR;
.LBB0_1142:
	s_add_u32 s0, s12, 0x4542000
	s_addc_u32 s1, s13, 0
	s_lshl_b32 s4, s4, 5
	s_and_b32 s11, s4, 0x60
	s_mov_b64 s[4:5], 0x80
	s_add_i32 m0, s21, 0x18000
	v_lshl_add_u64 v[6:7], v[6:7], 0, s[4:5]
	s_ashr_i32 s35, s94, 31
	s_ashr_i32 s36, s96, 31
	s_lshl_b32 s10, s3, 13
	s_lshl_b32 s16, s11, 7
	s_nop 0
	s_nop 0
	global_load_lds_dwordx4 v[6:7], off
	v_lshl_add_u64 v[4:5], v[4:5], 0, s[4:5]
	s_add_i32 m0, s21, 0x1a000
	s_add_i32 s37, s21, 0x8000
	s_add_i32 s38, s21, 0xa000
	global_load_lds_dwordx4 v[4:5], off
	v_lshl_add_u64 v[2:3], v[2:3], 0, s[4:5]
	s_mov_b32 m0, s37
	s_add_u32 s8, s24, 0x80080
	global_load_lds_dwordx4 v[2:3], off
	v_lshl_add_u64 v[0:1], v[0:1], 0, s[4:5]
	s_mov_b32 m0, s38
	s_addc_u32 s9, s25, 0
	global_load_lds_dwordx4 v[0:1], off
	s_add_i32 m0, s21, 0x1c000
	s_nop 0
	global_load_lds_dwordx4 v130, s[8:9]
	v_lshl_add_u64 v[0:1], s[8:9], 0, v[134:135]
	s_add_i32 m0, s21, 0x1e000
	s_sext_i32_i16 s43, s2
	global_load_lds_dwordx4 v[0:1], off
	v_lshlrev_b32_e32 v0, 1, v11
	v_lshlrev_b32_e32 v1, 6, v214
	s_movk_i32 s2, 0x3c0
	v_lshlrev_b32_e32 v2, 2, v214
	v_and_or_b32 v1, v1, s2, v0
	v_and_b32_e32 v2, 32, v2
	v_bitop3_b32 v148, s16, v1, v2 bitop3:0xf6
	v_lshlrev_b32_e32 v1, 9, v214
	v_and_b32_e32 v1, 0x70000, v1
	v_lshlrev_b32_e32 v2, 12, v10
	v_or3_b32 v1, v8, v1, v2
	v_lshlrev_b32_e32 v3, 2, v146
	v_add_u32_e32 v136, v1, v9
	v_lshlrev_b32_e32 v1, 5, v12
	v_lshl_or_b32 v0, v146, 6, v0
	v_and_b32_e32 v3, 32, v3
	s_waitcnt vmcnt(10)
	s_barrier
	s_waitcnt vmcnt(6)
	v_and_b32_e32 v1, 0xf0000, v1
	v_bitop3_b32 v0, v0, s10, v3 bitop3:0xde
	v_or3_b32 v1, v8, v1, v2
	s_add_i32 s40, 0, 0x10000
	s_add_i32 s41, 0, 0x14000
	s_mov_b32 s39, s96
	v_lshl_or_b32 v147, s3, 6, v146
	v_or_b32_e32 v149, s11, v11
	v_mov_b32_e32 v137, v131
	v_add_u32_e32 v138, v1, v9
	v_mov_b32_e32 v139, v131
	v_mov_b64_e32 v[140:141], 0x5ac
	v_mov_b64_e32 v[142:143], 0x5ab
	v_add_u32_e32 v150, s40, v148
	v_add_u32_e32 v151, 0, v0
	v_add_u32_e32 v153, s41, v148
	s_movk_i32 s42, 0x2c00
	s_barrier
	s_waitcnt vmcnt(0)

; #define PG8_STAGE(bufoff, gbase, voff) do { _Pragma("unroll") for (int _i = 0; _i < 2; ++_i) \
;         __builtin_amdgcn_global_load_lds((const unsigned*)((const char*)(gbase) + (voff)[_i]), (LAS unsigned*)(lds + (bufoff) + ldsw + _i * 8192), 16, 0, 0); } while (0)
; #define PG8_WAIT_V(n) asm volatile("s_waitcnt vmcnt(" #n ")" ::: "memory")
; #define PG8_BAR __builtin_amdgcn_s_barrier()
; template <class Epi>
; __device__ __forceinline__ void gemm_phase(LAS unsigned char* lds, const Gemm g, const StaticOrder& S, const Epi& E) {
;     ...
;     for (int i = 0; i < 2; ++i) { int R, C; stage_rc(tid * 16 + i * 8192, R, C); const int Rb = Epi::PERM ? ((R & ~31) + perm32(R & 31)) : R;
;         voffA[i] = (unsigned)(R * K + C) * 2u; voffB[i] = (unsigned)(Rb * K + C) * 2u; }
;     const size_t kstep = (size_t)(BK * 2);
;     const size_t hstep = (size_t)HALF * K * 2;
;     const size_t tstep = 2 * hstep;
;     const unsigned ldsw = (unsigned)wid * 1024u;
;     const int aoff = lds_byte(wr * 64 + fr, fq * 8), boff = lds_byte(wc * 32 + fr, fq * 8);
;     ...
;     const char* cA = (const char*)g.A + (size_t)cur.pm * tstep; const char* cB = (const char*)g.Bt + (size_t)cur.pn * tstep;
;     PG8_STAGE(PG8_SB(0, 0), cB, voffB); PG8_STAGE(PG8_SA(0, 0), cA, voffA); PG8_STAGE(PG8_SB(0, 1), cB + hstep, voffB); PG8_STAGE(PG8_SA(0, 1), cA + hstep, voffA);
;     if (wr == 1) PG8_BAR;
;     PG8_WAIT_V(4); PG8_BAR;
;     PG8_STAGE(PG8_SB(1, 0), cB + kstep, voffB); PG8_STAGE(PG8_SA(1, 0), cA + kstep, voffA); PG8_STAGE(PG8_SB(1, 1), cB + hstep + kstep, voffB);
;     PG8_WAIT_V(6); PG8_BAR;
.LBB0_1325:
	s_add_u32 s6, s12, 0x1a142000
	s_addc_u32 s7, s13, 0
	s_lshl_b32 s1, s1, 5
	s_mov_b64 s[16:17], 0x80
	s_and_b32 s1, s1, 0x60
	s_add_i32 m0, s29, 0x18000
	v_lshl_add_u64 v[6:7], v[6:7], 0, s[16:17]
	s_ashr_i32 s36, s94, 31
	s_ashr_i32 s37, s96, 31
	s_lshl_b32 s4, s0, 13
	s_lshl_b32 s5, s1, 7
	s_nop 0
	s_nop 0
	global_load_lds_dwordx4 v[6:7], off
	v_lshl_add_u64 v[4:5], v[4:5], 0, s[16:17]
	s_add_i32 m0, s29, 0x1a000
	s_add_i32 s38, s29, 0x8000
	s_add_i32 s39, s29, 0xa000
	global_load_lds_dwordx4 v[4:5], off
	v_lshl_add_u64 v[2:3], v[2:3], 0, s[16:17]
	s_mov_b32 m0, s38
	s_add_u32 s2, s24, 0x160080
	global_load_lds_dwordx4 v[2:3], off
	v_lshl_add_u64 v[0:1], v[0:1], 0, s[16:17]
	s_mov_b32 m0, s39
	s_addc_u32 s3, s25, 0
	global_load_lds_dwordx4 v[0:1], off
	s_add_i32 m0, s29, 0x1c000
	s_nop 0
	global_load_lds_dwordx4 v156, s[2:3]
	v_lshl_add_u64 v[0:1], s[2:3], 0, v[160:161]
	s_add_i32 m0, s29, 0x1e000
	s_movk_i32 s2, 0x3c0
	global_load_lds_dwordx4 v[0:1], off
	v_lshlrev_b32_e32 v0, 1, v10
	v_lshlrev_b32_e32 v1, 6, v214
	v_lshlrev_b32_e32 v2, 2, v214
	v_and_b32_e32 v153, 15, v214
	v_and_or_b32 v1, v1, s2, v0
	v_and_b32_e32 v2, 32, v2
	v_lshl_or_b32 v0, v153, 6, v0
	v_bitop3_b32 v183, s5, v1, v2 bitop3:0xf6
	s_waitcnt vmcnt(10)
	s_barrier
	s_waitcnt vmcnt(6)
	v_add_u16_e32 v1, v8, v9
	v_bitop3_b32 v0, v0, s4, v2 bitop3:0xde
	v_lshrrev_b16_e32 v1, 1, v1
	s_add_i32 s41, 0, 0x10000
	s_add_i32 s42, 0, 0x14000
	s_mov_b32 s40, s96
	v_lshl_or_b32 v182, s0, 6, v153
	v_or_b32_e32 v184, s1, v10
	v_add_lshl_u32 v162, v11, v1, 1
	v_mov_b32_e32 v163, v157
	v_add_lshl_u32 v164, v12, v1, 1
	v_mov_b32_e32 v165, v157
	v_mov_b64_e32 v[166:167], 0x100
	v_mov_b64_e32 v[168:169], 0xff
	v_add_u32_e32 v185, s41, v183
	v_add_u32_e32 v186, 0, v0
	v_add_u32_e32 v187, s42, v183
	s_movk_i32 s43, 0x2080
	s_mov_b32 s18, 0x3f9837f0
	s_mov_b64 s[20:21], 0x80000
	s_movk_i32 s44, 0x1ff0
	s_movk_i32 s45, 0x1fe0
	s_movk_i32 s46, 0x1fd0
	s_barrier
	s_branch .LBB0_1327
